# v26 with the indexer-score scratch stores at the default cache policy (no nt)
# speedup vs baseline: 1.0104x; 1.0042x over previous
.LBB0_797:
	ds_read_b128 v[2:5], v139
	ds_read_b128 v[18:21], v139 offset:32
	ds_read_b128 v[22:25], v139 offset:64
	ds_read_b128 v[26:29], v139 offset:96
	ds_read_b128 v[34:37], v139 offset:4608
	ds_read_b128 v[30:33], v139 offset:4640
	ds_read_b128 v[174:177], v139 offset:4672
	ds_read_b128 v[184:187], v139 offset:4704
	ds_read_b128 v[188:191], v139 offset:9216
	ds_read_b128 v[192:195], v139 offset:9248
	ds_read_b128 v[196:199], v139 offset:9280
	ds_read_b128 v[200:203], v139 offset:9312
	s_mov_b32 s8, s7
	s_add_i32 s7, s7, 4
	s_add_i32 s8, s8, 7
	s_waitcnt lgkmcnt(8)
	v_mfma_f32_32x32x16_bf16 v[2:17], v[58:61], v[2:5], 0
	s_cmp_ge_i32 s8, s6
	v_mfma_f32_32x32x16_bf16 v[2:17], v[54:57], v[18:21], v[2:17]
	v_mfma_f32_32x32x16_bf16 v[2:17], v[50:53], v[22:25], v[2:17]
	v_mfma_f32_32x32x16_bf16 v[2:17], v[62:65], v[26:29], v[2:17]
	s_waitcnt lgkmcnt(4)
	v_mfma_f32_32x32x16_bf16 v[34:49], v[58:61], v[34:37], 0
	s_nop 7
	s_nop 1
	v_max_f32_e32 v2, 0, v2
	v_fma_f32 v140, v120, v2, 0
	v_max_f32_e32 v2, 0, v10
	v_fma_f32 v141, v121, v2, 0
	v_mfma_f32_32x32x16_bf16 v[34:49], v[54:57], v[30:33], v[34:49]
	v_max_f32_e32 v2, 0, v3
	v_fmac_f32_e32 v140, v122, v2
	v_max_f32_e32 v2, 0, v11
	v_fmac_f32_e32 v141, v123, v2
	v_mfma_f32_32x32x16_bf16 v[34:49], v[50:53], v[174:177], v[34:49]
	v_max_f32_e32 v2, 0, v4
	v_fmac_f32_e32 v140, v124, v2
	v_max_f32_e32 v2, 0, v12
	v_fmac_f32_e32 v141, v125, v2
	v_mfma_f32_32x32x16_bf16 v[34:49], v[62:65], v[184:187], v[34:49]
	v_max_f32_e32 v2, 0, v5
	v_fmac_f32_e32 v140, v126, v2
	v_max_f32_e32 v2, 0, v13
	v_fmac_f32_e32 v141, v127, v2
	s_waitcnt lgkmcnt(0)
	v_mfma_f32_32x32x16_bf16 v[18:33], v[58:61], v[188:191], 0
	v_max_f32_e32 v2, 0, v6
	v_fmac_f32_e32 v140, v128, v2
	v_max_f32_e32 v2, 0, v14
	v_fmac_f32_e32 v141, v129, v2
	v_mfma_f32_32x32x16_bf16 v[18:33], v[54:57], v[192:195], v[18:33]
	v_max_f32_e32 v2, 0, v7
	v_fmac_f32_e32 v140, v130, v2
	v_max_f32_e32 v2, 0, v15
	v_fmac_f32_e32 v141, v131, v2
	v_mfma_f32_32x32x16_bf16 v[18:33], v[50:53], v[196:199], v[18:33]
	v_max_f32_e32 v2, 0, v8
	v_fmac_f32_e32 v140, v132, v2
	v_max_f32_e32 v2, 0, v16
	v_fmac_f32_e32 v141, v133, v2
	v_max_f32_e32 v2, 0, v9
	v_mfma_f32_32x32x16_bf16 v[18:33], v[62:65], v[200:203], v[18:33]
	ds_read_b128 v[110:113], v139 offset:13824
	ds_read_b128 v[106:109], v139 offset:13856
	ds_read_b128 v[102:105], v139 offset:13888
	ds_read_b128 v[98:101], v139 offset:13920
	v_fmac_f32_e32 v140, v134, v2
	v_max_f32_e32 v2, 0, v17
	v_fmac_f32_e32 v141, v135, v2
	v_max_f32_e32 v34, 0, v34
	s_waitcnt lgkmcnt(3)
	v_mfma_f32_32x32x16_bf16 v[2:17], v[58:61], v[110:113], 0
	s_nop 1
	v_max_f32_e32 v18, 0, v18
	v_add_u32_e32 v139, 0x4800, v139
	s_waitcnt lgkmcnt(2)
	v_mfma_f32_32x32x16_bf16 v[2:17], v[54:57], v[106:109], v[2:17]
	v_add_f32_e32 v106, 0, v141
	s_waitcnt lgkmcnt(1)
	v_mfma_f32_32x32x16_bf16 v[2:17], v[50:53], v[102:105], v[2:17]
	v_add_f32_e32 v102, 0, v140
	v_ashrrev_i32_e32 v103, 31, v102
	v_lshlrev_b64 v[104:105], 2, v[148:149]
	v_bitop3_b32 v107, v103, v102, s75 bitop3:0x36
	v_lshl_add_u64 v[102:103], v[116:117], 0, v[104:105]
	global_store_dword v[102:103], v107, off
	v_ashrrev_i32_e32 v107, 31, v106
	v_bitop3_b32 v106, v107, v106, s75 bitop3:0x36
	v_lshl_add_u64 v[208:209], v[118:119], 0, v[104:105]
	global_store_dword v[208:209], v106, off
	v_fma_f32 v104, v120, v34, 0
	v_max_f32_e32 v34, 0, v42
	v_fma_f32 v42, v121, v34, 0
	v_max_f32_e32 v34, 0, v35
	v_fmac_f32_e32 v104, v122, v34
	v_max_f32_e32 v34, 0, v43
	v_fmac_f32_e32 v42, v123, v34
	v_max_f32_e32 v34, 0, v36
	v_fmac_f32_e32 v104, v124, v34
	v_max_f32_e32 v34, 0, v44
	v_fmac_f32_e32 v42, v125, v34
	v_max_f32_e32 v34, 0, v37
	v_fmac_f32_e32 v104, v126, v34
	v_max_f32_e32 v34, 0, v45
	v_fmac_f32_e32 v42, v127, v34
	v_max_f32_e32 v34, 0, v38
	v_fmac_f32_e32 v104, v128, v34
	v_max_f32_e32 v34, 0, v46
	v_fmac_f32_e32 v42, v129, v34
	v_max_f32_e32 v34, 0, v39
	v_fmac_f32_e32 v104, v130, v34
	v_max_f32_e32 v34, 0, v47
	v_fmac_f32_e32 v42, v131, v34
	v_max_f32_e32 v34, 0, v40
	v_fmac_f32_e32 v104, v132, v34
	v_max_f32_e32 v34, 0, v48
	v_fmac_f32_e32 v42, v133, v34
	v_max_f32_e32 v34, 0, v41
	v_fmac_f32_e32 v104, v134, v34
	v_max_f32_e32 v34, 0, v49
	v_add_f32_e32 v35, 0, v104
	v_fmac_f32_e32 v42, v135, v34
	v_ashrrev_i32_e32 v37, 31, v35
	v_add_f32_e32 v36, 0, v42
	v_bitop3_b32 v37, v37, v35, s75 bitop3:0x36
	global_store_dword v[102:103], v37, off offset:128
	v_ashrrev_i32_e32 v37, 31, v36
	v_bitop3_b32 v36, v37, v36, s75 bitop3:0x36
	global_store_dword v[208:209], v36, off offset:128
	v_fma_f32 v34, v120, v18, 0
	v_max_f32_e32 v18, 0, v26
	v_fma_f32 v26, v121, v18, 0
	v_max_f32_e32 v18, 0, v19
	v_fmac_f32_e32 v34, v122, v18
	v_max_f32_e32 v18, 0, v27
	v_fmac_f32_e32 v26, v123, v18
	v_max_f32_e32 v18, 0, v20
	v_fmac_f32_e32 v34, v124, v18
	v_max_f32_e32 v18, 0, v28
	v_fmac_f32_e32 v26, v125, v18
	v_max_f32_e32 v18, 0, v21
	v_fmac_f32_e32 v34, v126, v18
	v_max_f32_e32 v18, 0, v29
	v_fmac_f32_e32 v26, v127, v18
	v_max_f32_e32 v18, 0, v22
	v_fmac_f32_e32 v34, v128, v18
	v_max_f32_e32 v18, 0, v30
	v_fmac_f32_e32 v26, v129, v18
	v_max_f32_e32 v18, 0, v23
	v_fmac_f32_e32 v34, v130, v18
	v_max_f32_e32 v18, 0, v31
	v_fmac_f32_e32 v26, v131, v18
	v_max_f32_e32 v18, 0, v24
	v_fmac_f32_e32 v34, v132, v18
	s_waitcnt lgkmcnt(0)
	v_mfma_f32_32x32x16_bf16 v[2:17], v[62:65], v[98:101], v[2:17]
	v_max_f32_e32 v18, 0, v32
	v_fmac_f32_e32 v26, v133, v18
	v_max_f32_e32 v18, 0, v25
	v_fmac_f32_e32 v34, v134, v18
	v_max_f32_e32 v18, 0, v33
	v_add_f32_e32 v19, 0, v34
	v_fmac_f32_e32 v26, v135, v18
	v_ashrrev_i32_e32 v21, 31, v19
	v_add_f32_e32 v20, 0, v26
	v_bitop3_b32 v21, v21, v19, s75 bitop3:0x36
	global_store_dword v[102:103], v21, off offset:256
	v_ashrrev_i32_e32 v21, 31, v20
	v_bitop3_b32 v20, v21, v20, s75 bitop3:0x36
	v_max_f32_e32 v2, 0, v2
	global_store_dword v[208:209], v20, off offset:256
	v_fma_f32 v18, v120, v2, 0
	v_max_f32_e32 v2, 0, v10
	v_fma_f32 v10, v121, v2, 0
	v_max_f32_e32 v2, 0, v3
	v_fmac_f32_e32 v18, v122, v2
	v_max_f32_e32 v2, 0, v11
	v_fmac_f32_e32 v10, v123, v2
	v_max_f32_e32 v2, 0, v4
	v_fmac_f32_e32 v18, v124, v2
	v_max_f32_e32 v2, 0, v12
	v_fmac_f32_e32 v10, v125, v2
	v_max_f32_e32 v2, 0, v5
	v_fmac_f32_e32 v18, v126, v2
	v_max_f32_e32 v2, 0, v13
	v_fmac_f32_e32 v10, v127, v2
	v_max_f32_e32 v2, 0, v6
	v_fmac_f32_e32 v18, v128, v2
	v_max_f32_e32 v2, 0, v14
	v_fmac_f32_e32 v10, v129, v2
	v_max_f32_e32 v2, 0, v7
	v_fmac_f32_e32 v18, v130, v2
	v_max_f32_e32 v2, 0, v15
	v_fmac_f32_e32 v10, v131, v2
	v_max_f32_e32 v2, 0, v8
	v_fmac_f32_e32 v18, v132, v2
	v_max_f32_e32 v2, 0, v16
	v_fmac_f32_e32 v10, v133, v2
	v_max_f32_e32 v2, 0, v9
	v_fmac_f32_e32 v18, v134, v2
	v_max_f32_e32 v2, 0, v17
	v_add_f32_e32 v3, 0, v18
	v_fmac_f32_e32 v10, v135, v2
	v_ashrrev_i32_e32 v5, 31, v3
	v_add_f32_e32 v4, 0, v10
	v_bitop3_b32 v5, v5, v3, s75 bitop3:0x36
	global_store_dword v[102:103], v5, off offset:384
	v_ashrrev_i32_e32 v5, 31, v4
	v_bitop3_b32 v4, v5, v4, s75 bitop3:0x36
	v_add_u32_e32 v148, 0x80, v148
	global_store_dword v[208:209], v4, off offset:384
	s_cbranch_scc0 .LBB0_797

.LBB0_800:
	ds_read_b128 v[2:5], v22
	ds_read_b128 v[18:21], v22 offset:32
	s_add_i32 s7, s7, 1
	s_cmp_ge_i32 s7, s6
	s_waitcnt lgkmcnt(1)
	v_mfma_f32_32x32x16_bf16 v[2:17], v[58:61], v[2:5], 0
	s_waitcnt lgkmcnt(0)
	v_mfma_f32_32x32x16_bf16 v[2:17], v[54:57], v[18:21], v[2:17]
	ds_read_b128 v[24:27], v22 offset:64
	ds_read_b128 v[18:21], v22 offset:96
	v_add_u32_e32 v22, 0x1200, v22
	s_waitcnt lgkmcnt(1)
	v_mfma_f32_32x32x16_bf16 v[2:17], v[50:53], v[24:27], v[2:17]
	v_lshlrev_b64 v[24:25], 2, v[148:149]
	v_add_u32_e32 v148, 32, v148
	v_lshl_add_u64 v[26:27], v[116:117], 0, v[24:25]
	v_lshl_add_u64 v[24:25], v[118:119], 0, v[24:25]
	s_waitcnt lgkmcnt(0)
	v_mfma_f32_32x32x16_bf16 v[2:17], v[62:65], v[18:21], v[2:17]
	s_nop 11
	v_max_f32_e32 v2, 0, v2
	v_max_f32_e32 v10, 0, v10
	v_max_f32_e32 v3, 0, v3
	v_fma_f32 v2, v120, v2, 0
	v_max_f32_e32 v11, 0, v11
	v_max_f32_e32 v4, 0, v4
	v_fma_f32 v10, v121, v10, 0
	v_fmac_f32_e32 v2, v122, v3
	v_max_f32_e32 v12, 0, v12
	v_max_f32_e32 v5, 0, v5
	v_fmac_f32_e32 v10, v123, v11
	v_fmac_f32_e32 v2, v124, v4
	v_max_f32_e32 v13, 0, v13
	v_max_f32_e32 v6, 0, v6
	v_fmac_f32_e32 v10, v125, v12
	v_fmac_f32_e32 v2, v126, v5
	v_max_f32_e32 v14, 0, v14
	v_max_f32_e32 v7, 0, v7
	v_fmac_f32_e32 v10, v127, v13
	v_fmac_f32_e32 v2, v128, v6
	v_max_f32_e32 v15, 0, v15
	v_max_f32_e32 v8, 0, v8
	v_fmac_f32_e32 v10, v129, v14
	v_fmac_f32_e32 v2, v130, v7
	v_max_f32_e32 v16, 0, v16
	v_max_f32_e32 v9, 0, v9
	v_fmac_f32_e32 v10, v131, v15
	v_fmac_f32_e32 v2, v132, v8
	v_max_f32_e32 v17, 0, v17
	v_fmac_f32_e32 v10, v133, v16
	v_fmac_f32_e32 v2, v134, v9
	v_fmac_f32_e32 v10, v135, v17
	v_add_f32_e32 v2, 0, v2
	v_add_f32_e32 v3, 0, v10
	v_ashrrev_i32_e32 v4, 31, v2
	v_ashrrev_i32_e32 v5, 31, v3
	v_bitop3_b32 v2, v4, v2, s75 bitop3:0x36
	v_bitop3_b32 v3, v5, v3, s75 bitop3:0x36
	global_store_dword v[26:27], v2, off
	global_store_dword v[24:25], v3, off
	s_cbranch_scc0 .LBB0_800
	s_branch .LBB0_792

.LBB0_3056:
	ds_read_b128 v[2:5], v161
	ds_read_b128 v[114:117], v161 offset:32
	ds_read_b128 v[18:21], v161 offset:4608
	ds_read_b128 v[118:121], v161 offset:4640
	ds_read_b128 v[34:37], v161 offset:9216
	ds_read_b128 v[122:125], v161 offset:9248
	ds_read_b128 v[50:53], v161 offset:13824
	ds_read_b128 v[132:135], v161 offset:13856
	s_waitcnt lgkmcnt(7)
	v_mfma_f32_32x32x16_bf16 v[2:17], v[74:77], v[2:5], 0
	s_mov_b32 s10, s9
	s_add_i32 s9, s9, 4
	s_add_i32 s10, s10, 7
	s_cmp_ge_i32 s10, s8
	s_waitcnt lgkmcnt(5)
	v_mfma_f32_32x32x16_bf16 v[18:33], v[74:77], v[18:21], 0
	s_waitcnt lgkmcnt(1)
	v_mfma_f32_32x32x16_bf16 v[50:65], v[74:77], v[50:53], 0
	v_mfma_f32_32x32x16_bf16 v[34:49], v[74:77], v[34:37], 0
	v_mfma_f32_32x32x16_bf16 v[2:17], v[70:73], v[114:117], v[2:17]
	v_mfma_f32_32x32x16_bf16 v[18:33], v[70:73], v[118:121], v[18:33]
	s_waitcnt lgkmcnt(0)
	v_mfma_f32_32x32x16_bf16 v[50:65], v[70:73], v[132:135], v[50:65]
	ds_read_b128 v[114:117], v161 offset:64
	ds_read_b128 v[132:135], v161 offset:96
	v_mfma_f32_32x32x16_bf16 v[34:49], v[70:73], v[122:125], v[34:49]
	s_waitcnt lgkmcnt(1)
	v_mfma_f32_32x32x16_bf16 v[2:17], v[66:69], v[114:117], v[2:17]
	ds_read_b128 v[114:117], v161 offset:4672
	ds_read_b128 v[122:125], v161 offset:4704
	s_waitcnt lgkmcnt(1)
	v_mfma_f32_32x32x16_bf16 v[18:33], v[66:69], v[114:117], v[18:33]
	ds_read_b128 v[114:117], v161 offset:9280
	ds_read_b128 v[118:121], v161 offset:9312
	s_waitcnt lgkmcnt(1)
	v_mfma_f32_32x32x16_bf16 v[34:49], v[66:69], v[114:117], v[34:49]
	ds_read_b128 v[162:165], v161 offset:13888
	ds_read_b128 v[114:117], v161 offset:13920
	v_add_u32_e32 v161, 0x4800, v161
	s_waitcnt lgkmcnt(1)
	v_mfma_f32_32x32x16_bf16 v[50:65], v[66:69], v[162:165], v[50:65]
	v_mfma_f32_32x32x16_bf16 v[2:17], v[78:81], v[132:135], v[2:17]
	v_lshlrev_b64 v[132:133], 2, v[148:149]
	v_mfma_f32_32x32x16_bf16 v[18:33], v[78:81], v[122:125], v[18:33]
	s_nop 7
	s_nop 1
	v_max_f32_e32 v2, 0, v2
	v_max_f32_e32 v10, 0, v10
	v_mfma_f32_32x32x16_bf16 v[34:49], v[78:81], v[118:121], v[34:49]
	v_max_f32_e32 v3, 0, v3
	v_max_f32_e32 v18, 0, v18
	v_max_f32_e32 v26, 0, v26
	s_waitcnt lgkmcnt(0)
	v_mfma_f32_32x32x16_bf16 v[50:65], v[78:81], v[114:117], v[50:65]
	s_nop 2
	s_nop 3
	v_max_f32_e32 v34, 0, v34
	v_max_f32_e32 v42, 0, v42
	v_fma_f32 v2, v138, v2, 0
	s_nop 1
	v_max_f32_e32 v50, 0, v50
	v_max_f32_e32 v58, 0, v58
	v_max_f32_e32 v11, 0, v11
	v_max_f32_e32 v4, 0, v4
	v_max_f32_e32 v19, 0, v19
	v_max_f32_e32 v27, 0, v27
	v_max_f32_e32 v35, 0, v35
	v_max_f32_e32 v43, 0, v43
	v_max_f32_e32 v51, 0, v51
	v_max_f32_e32 v59, 0, v59
	v_fma_f32 v10, v139, v10, 0
	v_fma_f32 v18, v138, v18, 0
	v_fma_f32 v26, v139, v26, 0
	v_fma_f32 v34, v138, v34, 0
	v_fma_f32 v42, v139, v42, 0
	v_fma_f32 v50, v138, v50, 0
	v_fma_f32 v58, v139, v58, 0
	v_fmac_f32_e32 v2, v140, v3
	v_max_f32_e32 v12, 0, v12
	v_max_f32_e32 v5, 0, v5
	v_max_f32_e32 v20, 0, v20
	v_max_f32_e32 v28, 0, v28
	v_max_f32_e32 v36, 0, v36
	v_max_f32_e32 v44, 0, v44
	v_max_f32_e32 v52, 0, v52
	v_max_f32_e32 v60, 0, v60
	v_fmac_f32_e32 v10, v141, v11
	v_fmac_f32_e32 v18, v140, v19
	v_fmac_f32_e32 v26, v141, v27
	v_fmac_f32_e32 v34, v140, v35
	v_fmac_f32_e32 v42, v141, v43
	v_fmac_f32_e32 v50, v140, v51
	v_fmac_f32_e32 v58, v141, v59
	v_fmac_f32_e32 v2, v142, v4
	v_max_f32_e32 v13, 0, v13
	v_max_f32_e32 v6, 0, v6
	v_max_f32_e32 v21, 0, v21
	v_max_f32_e32 v29, 0, v29
	v_max_f32_e32 v37, 0, v37
	v_max_f32_e32 v45, 0, v45
	v_max_f32_e32 v53, 0, v53
	v_max_f32_e32 v61, 0, v61
	v_fmac_f32_e32 v10, v143, v12
	v_fmac_f32_e32 v18, v142, v20
	v_fmac_f32_e32 v26, v143, v28
	v_fmac_f32_e32 v34, v142, v36
	v_fmac_f32_e32 v42, v143, v44
	v_fmac_f32_e32 v50, v142, v52
	v_fmac_f32_e32 v58, v143, v60
	v_fmac_f32_e32 v2, v144, v5
	v_max_f32_e32 v14, 0, v14
	v_max_f32_e32 v7, 0, v7
	v_max_f32_e32 v22, 0, v22
	v_max_f32_e32 v30, 0, v30
	v_max_f32_e32 v38, 0, v38
	v_max_f32_e32 v46, 0, v46
	v_max_f32_e32 v54, 0, v54
	v_max_f32_e32 v62, 0, v62
	v_fmac_f32_e32 v10, v145, v13
	v_fmac_f32_e32 v18, v144, v21
	v_fmac_f32_e32 v26, v145, v29
	v_fmac_f32_e32 v34, v144, v37
	v_fmac_f32_e32 v42, v145, v45
	v_fmac_f32_e32 v50, v144, v53
	v_fmac_f32_e32 v58, v145, v61
	v_fmac_f32_e32 v2, v150, v6
	v_max_f32_e32 v15, 0, v15
	v_max_f32_e32 v8, 0, v8
	v_max_f32_e32 v23, 0, v23
	v_max_f32_e32 v31, 0, v31
	v_max_f32_e32 v39, 0, v39
	v_max_f32_e32 v47, 0, v47
	v_max_f32_e32 v55, 0, v55
	v_max_f32_e32 v63, 0, v63
	v_fmac_f32_e32 v10, v151, v14
	v_fmac_f32_e32 v18, v150, v22
	v_fmac_f32_e32 v26, v151, v30
	v_fmac_f32_e32 v34, v150, v38
	v_fmac_f32_e32 v42, v151, v46
	v_fmac_f32_e32 v50, v150, v54
	v_fmac_f32_e32 v58, v151, v62
	v_fmac_f32_e32 v2, v152, v7
	v_max_f32_e32 v16, 0, v16
	v_max_f32_e32 v9, 0, v9
	v_max_f32_e32 v24, 0, v24
	v_max_f32_e32 v32, 0, v32
	v_max_f32_e32 v40, 0, v40
	v_max_f32_e32 v48, 0, v48
	v_max_f32_e32 v56, 0, v56
	v_max_f32_e32 v64, 0, v64
	v_fmac_f32_e32 v10, v153, v15
	v_fmac_f32_e32 v18, v152, v23
	v_fmac_f32_e32 v26, v153, v31
	v_fmac_f32_e32 v34, v152, v39
	v_fmac_f32_e32 v42, v153, v47
	v_fmac_f32_e32 v50, v152, v55
	v_fmac_f32_e32 v58, v153, v63
	v_fmac_f32_e32 v2, v154, v8
	v_max_f32_e32 v17, 0, v17
	v_max_f32_e32 v25, 0, v25
	v_max_f32_e32 v33, 0, v33
	v_max_f32_e32 v41, 0, v41
	v_max_f32_e32 v49, 0, v49
	v_max_f32_e32 v57, 0, v57
	v_max_f32_e32 v65, 0, v65
	v_fmac_f32_e32 v10, v155, v16
	v_fmac_f32_e32 v18, v154, v24
	v_fmac_f32_e32 v26, v155, v32
	v_fmac_f32_e32 v34, v154, v40
	v_fmac_f32_e32 v42, v155, v48
	v_fmac_f32_e32 v50, v154, v56
	v_fmac_f32_e32 v58, v155, v64
	v_fmac_f32_e32 v2, v156, v9
	v_fmac_f32_e32 v10, v157, v17
	v_fmac_f32_e32 v18, v156, v25
	v_fmac_f32_e32 v26, v157, v33
	v_fmac_f32_e32 v34, v156, v41
	v_fmac_f32_e32 v42, v157, v49
	v_fmac_f32_e32 v50, v156, v57
	v_fmac_f32_e32 v58, v157, v65
	v_add_f32_e32 v2, 0, v2
	v_add_f32_e32 v3, 0, v10
	v_add_f32_e32 v4, 0, v18
	v_add_f32_e32 v5, 0, v26
	v_add_f32_e32 v6, 0, v34
	v_add_f32_e32 v7, 0, v42
	v_add_f32_e32 v8, 0, v50
	v_add_f32_e32 v9, 0, v58
	v_ashrrev_i32_e32 v10, 31, v2
	v_add_u32_e32 v148, 0x80, v148
	v_lshl_add_u64 v[122:123], v[128:129], 0, v[132:133]
	v_ashrrev_i32_e32 v11, 31, v3
	v_ashrrev_i32_e32 v12, 31, v4
	v_ashrrev_i32_e32 v13, 31, v5
	v_ashrrev_i32_e32 v14, 31, v6
	v_ashrrev_i32_e32 v15, 31, v7
	v_ashrrev_i32_e32 v16, 31, v8
	v_ashrrev_i32_e32 v17, 31, v9
	v_bitop3_b32 v2, v10, v2, s57 bitop3:0x36
	v_lshl_add_u64 v[118:119], v[130:131], 0, v[132:133]
	v_bitop3_b32 v3, v11, v3, s57 bitop3:0x36
	v_bitop3_b32 v4, v12, v4, s57 bitop3:0x36
	v_bitop3_b32 v5, v13, v5, s57 bitop3:0x36
	v_bitop3_b32 v6, v14, v6, s57 bitop3:0x36
	v_bitop3_b32 v7, v15, v7, s57 bitop3:0x36
	v_bitop3_b32 v8, v16, v8, s57 bitop3:0x36
	v_bitop3_b32 v9, v17, v9, s57 bitop3:0x36
	global_store_dword v[122:123], v2, off
	global_store_dword v[118:119], v3, off
	global_store_dword v[122:123], v4, off offset:128
	global_store_dword v[118:119], v5, off offset:128
	global_store_dword v[122:123], v6, off offset:256
	global_store_dword v[118:119], v7, off offset:256
	global_store_dword v[122:123], v8, off offset:384
	global_store_dword v[118:119], v9, off offset:384
	s_cbranch_scc0 .LBB0_3056

.LBB0_3059:
	ds_read_b128 v[2:5], v22
	ds_read_b128 v[18:21], v22 offset:32
	s_add_i32 s9, s9, 1
	s_cmp_ge_i32 s9, s8
	s_waitcnt lgkmcnt(1)
	v_mfma_f32_32x32x16_bf16 v[2:17], v[74:77], v[2:5], 0
	s_waitcnt lgkmcnt(0)
	v_mfma_f32_32x32x16_bf16 v[2:17], v[70:73], v[18:21], v[2:17]
	ds_read_b128 v[24:27], v22 offset:64
	ds_read_b128 v[18:21], v22 offset:96
	v_add_u32_e32 v22, 0x1200, v22
	s_waitcnt lgkmcnt(1)
	v_mfma_f32_32x32x16_bf16 v[2:17], v[66:69], v[24:27], v[2:17]
	v_lshlrev_b64 v[24:25], 2, v[148:149]
	v_add_u32_e32 v148, 32, v148
	v_lshl_add_u64 v[26:27], v[128:129], 0, v[24:25]
	v_lshl_add_u64 v[24:25], v[130:131], 0, v[24:25]
	s_waitcnt lgkmcnt(0)
	v_mfma_f32_32x32x16_bf16 v[2:17], v[78:81], v[18:21], v[2:17]
	s_nop 11
	v_max_f32_e32 v2, 0, v2
	v_max_f32_e32 v10, 0, v10
	v_max_f32_e32 v3, 0, v3
	v_fma_f32 v2, v138, v2, 0
	v_max_f32_e32 v11, 0, v11
	v_max_f32_e32 v4, 0, v4
	v_fma_f32 v10, v139, v10, 0
	v_fmac_f32_e32 v2, v140, v3
	v_max_f32_e32 v12, 0, v12
	v_max_f32_e32 v5, 0, v5
	v_fmac_f32_e32 v10, v141, v11
	v_fmac_f32_e32 v2, v142, v4
	v_max_f32_e32 v13, 0, v13
	v_max_f32_e32 v6, 0, v6
	v_fmac_f32_e32 v10, v143, v12
	v_fmac_f32_e32 v2, v144, v5
	v_max_f32_e32 v14, 0, v14
	v_max_f32_e32 v7, 0, v7
	v_fmac_f32_e32 v10, v145, v13
	v_fmac_f32_e32 v2, v150, v6
	v_max_f32_e32 v15, 0, v15
	v_max_f32_e32 v8, 0, v8
	v_fmac_f32_e32 v10, v151, v14
	v_fmac_f32_e32 v2, v152, v7
	v_max_f32_e32 v16, 0, v16
	v_max_f32_e32 v9, 0, v9
	v_fmac_f32_e32 v10, v153, v15
	v_fmac_f32_e32 v2, v154, v8
	v_max_f32_e32 v17, 0, v17
	v_fmac_f32_e32 v10, v155, v16
	v_fmac_f32_e32 v2, v156, v9
	v_fmac_f32_e32 v10, v157, v17
	v_add_f32_e32 v2, 0, v2
	v_add_f32_e32 v3, 0, v10
	v_ashrrev_i32_e32 v4, 31, v2
	v_ashrrev_i32_e32 v5, 31, v3
	v_bitop3_b32 v2, v4, v2, s57 bitop3:0x36
	v_bitop3_b32 v3, v5, v3, s57 bitop3:0x36
	global_store_dword v[26:27], v2, off
	global_store_dword v[24:25], v3, off
	s_cbranch_scc0 .LBB0_3059
	s_branch .LBB0_3051
